# all GEMM s_setprio flips removed plus ONE static s_setprio 1 for waves 4-7 at kernel entry
# baseline (speedup 1.0000x reference)
; #define LAS __attribute__((address_space(3)))
; __global__ void __launch_bounds__(NTHR) hybrid_encoder_fwd(Params P) {
;     extern __shared__ __attribute__((aligned(16))) unsigned char lds_raw[];
;     LAS unsigned char* lds = (LAS unsigned char*)lds_raw;
;     cg::grid_group grid = cg::this_grid();
;     if (threadIdx.x == 0) { *(volatile LAS unsigned*)(lds + LDS_XB) = 0u; *(volatile LAS unsigned*)(lds + LDS_XB + 4) = 0u; }
;     __syncthreads();
;     const XcdBarrier xb = xcd_barrier_post((unsigned*)P.ws, (volatile LAS unsigned*)(lds + LDS_XB));
;     const int tid = threadIdx.x, lane = tid & 63, wid = __builtin_amdgcn_readfirstlane(tid >> 6);
_Z18hybrid_encoder_fwd6Params:
	s_load_dwordx2 s[96:97], s[0:1], 0xb0
	s_load_dwordx4 s[4:7], s[0:1], 0xa0
	s_load_dwordx8 s[12:19], s[0:1], 0x80
	s_load_dword s3, s[0:1], 0xc8
	s_load_dwordx2 s[94:95], s[0:1], 0xc0
	v_and_b32_e32 v200, 0x3ff, v0
	s_waitcnt lgkmcnt(0)
	v_readfirstlane_b32 s98, v200
	s_lshr_b32 s98, s98, 6
	s_cmp_ge_u32 s98, 4
	s_cbranch_scc0 .Lprio_done
	s_setprio 1
.Lprio_done:
	v_writelane_b32 v253, s4, 0
	s_nop 1
	v_writelane_b32 v253, s5, 1
	v_writelane_b32 v253, s6, 2
	v_writelane_b32 v253, s7, 3
	s_add_u32 s4, s0, 0xc0
	v_writelane_b32 v253, s3, 4
	s_addc_u32 s5, s1, 0
	v_writelane_b32 v253, s4, 6
	v_cmp_eq_u32_e64 s[6:7], 0, v200
	s_nop 0
	v_writelane_b32 v253, s5, 7
	s_mov_b64 s[4:5], exec
	v_writelane_b32 v253, s6, 8
	s_nop 1
	v_writelane_b32 v253, s7, 9
	s_and_b64 s[6:7], s[4:5], s[6:7]
	s_mov_b64 exec, s[6:7]
	s_cbranch_execz .LBB0_2
	s_add_i32 s3, 0, 0x25af0
	v_mov_b32_e32 v1, 0
	v_mov_b32_e32 v2, s3
	s_add_i32 s3, 0, 0x25af4
	ds_write_b32 v2, v1
	v_mov_b32_e32 v2, s3
	ds_write_b32 v2, v1
